# cache-policy hints: nt on phase-1 bf16 epilogue stores and on the widened output stores (on top of v41)
# baseline (speedup 1.0000x reference)
.LBB0_135:
	v_lshlrev_b32_e32 v2, 4, v1
	v_ashrrev_i32_e32 v4, 3, v11
	v_and_b32_e32 v2, 0x70, v2
	v_mov_b32_e32 v3, v0
	v_lshl_add_u64 v[6:7], s[2:3], 0, v[2:3]
	v_lshrrev_b32_e32 v3, 2, v4
	v_xor_b32_e32 v3, v3, v1
	v_add_u32_e32 v12, s52, v4
	v_lshlrev_b32_e32 v3, 4, v3
	v_lshlrev_b32_e32 v2, 7, v12
	v_and_b32_e32 v3, 0x70, v3
	s_waitcnt lgkmcnt(0)
	s_barrier
	v_add3_u32 v2, s53, v2, v3
	ds_read_b128 v[150:153], v2
	v_mul_lo_u32 v8, s4, v12
	v_mov_b32_e32 v9, v0
	v_lshl_add_u64 v[166:167], v[8:9], 1, v[6:7]
	s_lshl_b32 s0, s4, 3
	v_add_u32_e32 v8, s0, v8
	v_lshl_add_u64 v[168:169], v[8:9], 1, v[6:7]
	v_add_u32_e32 v2, 8, v12
	v_lshlrev_b32_e32 v3, 7, v2
	v_lshrrev_b32_e32 v2, 2, v2
	v_xor_b32_e32 v2, v2, v1
	v_lshlrev_b32_e32 v2, 4, v2
	v_and_b32_e32 v2, 0x70, v2
	v_add3_u32 v2, s53, v3, v2
	ds_read_b128 v[154:157], v2
	v_add_u32_e32 v8, s0, v8
	s_nop 1
	v_add_u32_e32 v2, 16, v12
	v_lshlrev_b32_e32 v3, 7, v2
	v_lshrrev_b32_e32 v2, 2, v2
	v_xor_b32_e32 v2, v2, v1
	v_lshlrev_b32_e32 v2, 4, v2
	v_and_b32_e32 v2, 0x70, v2
	v_add3_u32 v2, s53, v3, v2
	ds_read_b128 v[158:161], v2
	v_lshl_add_u64 v[170:171], v[8:9], 1, v[6:7]
	v_add_u32_e32 v8, s0, v8
	v_lshl_add_u64 v[172:173], v[8:9], 1, v[6:7]
	s_nop 1
	v_add_u32_e32 v2, 24, v12
	v_lshlrev_b32_e32 v3, 7, v2
	v_lshrrev_b32_e32 v2, 2, v2
	v_xor_b32_e32 v1, v2, v1
	v_lshlrev_b32_e32 v1, 4, v1
	v_and_b32_e32 v1, 0x70, v1
	v_add3_u32 v1, s53, v3, v1
	ds_read_b128 v[162:165], v1
	s_waitcnt lgkmcnt(3)
	global_store_dwordx4 v[166:167], v[150:153], off nt
	s_waitcnt lgkmcnt(2)
	global_store_dwordx4 v[168:169], v[154:157], off nt
	s_waitcnt lgkmcnt(1)
	global_store_dwordx4 v[170:171], v[158:161], off nt
	s_waitcnt lgkmcnt(0)
	global_store_dwordx4 v[172:173], v[162:165], off nt
	s_waitcnt lgkmcnt(0)
	s_barrier

.LBB0_221:
	s_lshl_b32 s52, s45, 5
	s_cmp_eq_u32 s68, 10
	s_cselect_b64 s[88:89], -1, 0
	s_cmp_lg_u32 s68, 10
	s_cselect_b64 s[60:61], -1, 0
	s_and_b64 s[0:1], s[10:11], exec
	s_mov_b32 s0, 0xb080000
	s_cselect_b32 s19, s0, 0xa600000
	s_cmp_gt_i32 s45, 1
	s_cselect_b64 s[66:67], -1, 0
	s_cmp_eq_u32 s45, 2
	s_cselect_b64 s[20:21], -1, 0
	s_lshl_b32 s2, s17, 7
	s_add_i32 s3, s2, 0xffc00000
	s_and_b64 s[0:1], s[10:11], exec
	v_mov_b32_e32 v143, v249
	v_mov_b32_e32 v142, v1
	s_mov_b32 s0, 0x2c00000
	v_cndmask_b32_e64 v131, 0, 1, s[12:13]
	v_lshlrev_b32_e32 v130, 2, v143
	s_cselect_b32 s24, s3, s2
	s_cselect_b32 s55, s0, 0x2180000
	v_add_u32_e32 v132, s52, v130
	s_mov_b64 s[2:3], -1
	s_and_b64 vcc, exec, s[60:61]
	v_cmp_ne_u32_e64 s[0:1], 1, v131
	s_cbranch_vccz .LBB0_248
	s_and_b64 vcc, exec, s[0:1]
	s_cbranch_vccnz .LBB0_247
	s_lshl_b32 s4, s17, 6
	v_readlane_b32 s76, v251, 3
	s_add_i32 s5, s4, 0xffe00000
	v_readlane_b32 s77, v251, 4
	v_readlane_b32 s78, v251, 5
	v_readlane_b32 s79, v251, 6
	v_readlane_b32 s80, v251, 7
	v_readlane_b32 s81, v251, 8
	s_and_b64 s[2:3], s[10:11], exec
	v_readlane_b32 s82, v251, 9
	v_readlane_b32 s83, v251, 10
	s_mov_b64 s[76:77], s[80:81]
	s_cselect_b32 s2, s5, s4
	s_lshl_b32 s4, s17, 3
	s_mov_b64 s[78:79], s[82:83]
	s_mov_b32 s3, s25
	s_add_u32 s12, s78, s19
	s_addc_u32 s13, s79, 0
	s_lshl_b64 s[2:3], s[2:3], 2
	s_mov_b32 s5, s25
	s_add_u32 s2, s12, s2
	s_addc_u32 s3, s13, s3
	s_lshl_b64 s[4:5], s[4:5], 2
	v_readlane_b32 s12, v252, 47
	v_readlane_b32 s13, v252, 48
	s_add_u32 s4, s12, s4
	s_addc_u32 s5, s13, s5
	v_cmp_gt_i32_e32 vcc, 2, v143
	v_ashrrev_i32_e32 v131, 31, v130
	s_and_b64 s[12:13], s[20:21], vcc
	v_lshlrev_b32_e32 v134, 3, v142
	v_lshl_add_u64 v[136:137], v[130:131], 2, s[4:5]
	s_mov_b64 s[50:51], -1
	s_and_b64 vcc, exec, s[66:67]
	s_cbranch_vccz .LBB0_227
	s_and_saveexec_b64 s[50:51], s[12:13]
	s_cbranch_execz .LBB0_226
	s_mov_b32 s4, 0x3d3504f3
	v_mov_b32_e32 v135, v0
	v_pk_mul_f32 v[140:141], v[100:101], s[4:5] op_sel_hi:[1,0]
	v_pk_mul_f32 v[138:139], v[98:99], s[4:5] op_sel_hi:[1,0]
	v_lshl_add_u64 v[144:145], v[134:135], 2, v[136:137]
	global_store_dwordx4 v[144:145], v[138:141], off nt

.LBB0_229:
	v_cndmask_b32_e64 v131, 0, 1, s[66:67]
	v_cmp_ne_u32_e64 s[2:3], 1, v131
	s_andn2_b64 vcc, exec, s[66:67]
	s_mov_b64 s[50:51], -1
	s_cbranch_vccnz .LBB0_241
	s_and_saveexec_b64 s[50:51], s[12:13]
	s_cbranch_execz .LBB0_232
	s_mov_b32 s4, 0x3d3504f3
	v_add_u32_e32 v148, 0x80, v134
	v_mov_b32_e32 v149, v0
	v_pk_mul_f32 v[146:147], v[104:105], s[4:5] op_sel_hi:[1,0]
	v_pk_mul_f32 v[144:145], v[102:103], s[4:5] op_sel_hi:[1,0]
	v_lshl_add_u64 v[148:149], v[148:149], 2, v[136:137]
	global_store_dwordx4 v[148:149], v[144:147], off nt

.LBB0_234:
	s_and_saveexec_b64 s[50:51], s[12:13]
	s_cbranch_execz .LBB0_236
	s_mov_b32 s4, 0x3d3504f3
	v_add_u32_e32 v148, 0x100, v134
	v_mov_b32_e32 v149, v0
	v_pk_mul_f32 v[146:147], v[108:109], s[4:5] op_sel_hi:[1,0]
	v_pk_mul_f32 v[144:145], v[106:107], s[4:5] op_sel_hi:[1,0]
	v_lshl_add_u64 v[148:149], v[148:149], 2, v[136:137]
	global_store_dwordx4 v[148:149], v[144:147], off nt

.LBB0_238:
	s_and_saveexec_b64 s[2:3], s[12:13]
	s_cbranch_execz .LBB0_240
	s_mov_b32 s4, 0x3d3504f3
	v_add_u32_e32 v134, 0x180, v134
	v_mov_b32_e32 v135, v0
	v_pk_mul_f32 v[146:147], v[120:121], s[4:5] op_sel_hi:[1,0]
	v_pk_mul_f32 v[144:145], v[118:119], s[4:5] op_sel_hi:[1,0]
	v_lshl_add_u64 v[134:135], v[134:135], 2, v[136:137]
	global_store_dwordx4 v[134:135], v[144:147], off nt

.LBB0_286:
	s_waitcnt lgkmcnt(0)
	s_barrier
	v_and_b32_e32 v131, 15, v142
	v_readlane_b32 s12, v251, 51
	v_cmp_gt_u32_e32 vcc, 8, v131
	v_readlane_b32 s13, v251, 52
	s_or_b64 s[80:81], s[12:13], vcc
	s_and_saveexec_b64 s[12:13], s[80:81]
	s_cbranch_execz .LBB0_288
	v_lshrrev_b32_e32 v131, 3, v131
	v_mul_u32_u24_e32 v131, s76, v131
	v_and_b32_e32 v135, s69, v142
	v_lshlrev_b32_e32 v131, 1, v131
	v_lshl_or_b32 v136, v135, 4, v131
	v_ashrrev_i32_e32 v131, 4, v133
	v_add_u32_e32 v135, s75, v131
	v_xor_b32_e32 v131, v131, v142
	v_mov_b32_e32 v137, v0
	v_lshlrev_b32_e32 v131, 4, v131
	v_lshl_add_u64 v[140:141], s[2:3], 0, v[136:137]
	v_lshlrev_b32_e32 v136, 8, v135
	v_and_b32_e32 v131, 0xf0, v131
	v_add3_u32 v131, s53, v131, v136
	ds_read_b128 v[150:153], v131
	v_mul_lo_u32 v144, s65, v135
	v_mov_b32_e32 v145, v0
	v_lshl_add_u64 v[166:167], v[144:145], 1, v[140:141]
	v_add_u32_e32 v131, 4, v135
	s_lshl_b32 s2, s65, 2
	v_add_u32_e32 v144, s2, v144
	v_lshlrev_b32_e32 v136, 8, v131
	v_xor_b32_e32 v131, v131, v142
	v_lshlrev_b32_e32 v131, 4, v131
	v_and_b32_e32 v131, 0xf0, v131
	v_add3_u32 v131, s53, v131, v136
	ds_read_b128 v[154:157], v131
	v_lshl_add_u64 v[168:169], v[144:145], 1, v[140:141]
	v_add_u32_e32 v131, 8, v135
	v_add_u32_e32 v144, s2, v144
	v_lshl_add_u64 v[170:171], v[144:145], 1, v[140:141]
	s_nop 0
	v_lshlrev_b32_e32 v136, 8, v131
	v_xor_b32_e32 v131, v131, v142
	v_lshlrev_b32_e32 v131, 4, v131
	v_and_b32_e32 v131, 0xf0, v131
	v_add3_u32 v131, s53, v131, v136
	ds_read_b128 v[158:161], v131
	v_add_u32_e32 v131, 12, v135
	v_lshlrev_b32_e32 v135, 8, v131
	v_xor_b32_e32 v131, v131, v142
	v_lshlrev_b32_e32 v131, 4, v131
	v_and_b32_e32 v131, 0xf0, v131
	v_add3_u32 v131, s53, v131, v135
	s_nop 0
	v_add_u32_e32 v136, s2, v144
	v_mov_b32_e32 v137, v0
	v_lshl_add_u64 v[172:173], v[136:137], 1, v[140:141]
	ds_read_b128 v[162:165], v131
	s_waitcnt lgkmcnt(3)
	global_store_dwordx4 v[166:167], v[150:153], off nt
	s_waitcnt lgkmcnt(2)
	global_store_dwordx4 v[168:169], v[154:157], off nt
	s_waitcnt lgkmcnt(1)
	global_store_dwordx4 v[170:171], v[158:161], off nt
	s_waitcnt lgkmcnt(0)
	global_store_dwordx4 v[172:173], v[162:165], off nt

.LBB0_302:
	v_lshlrev_b32_e32 v98, 4, v142
	v_ashrrev_i32_e32 v100, 3, v133
	v_and_b32_e32 v98, 0x70, v98
	v_mov_b32_e32 v99, v0
	v_lshl_add_u64 v[102:103], s[2:3], 0, v[98:99]
	v_lshrrev_b32_e32 v99, 2, v100
	v_xor_b32_e32 v99, v99, v142
	v_add_u32_e32 v108, s52, v100
	v_lshlrev_b32_e32 v99, 4, v99
	v_lshlrev_b32_e32 v98, 7, v108
	v_and_b32_e32 v99, 0x70, v99
	s_waitcnt lgkmcnt(0)
	s_barrier
	v_add3_u32 v98, s53, v98, v99
	ds_read_b128 v[150:153], v98
	v_mul_lo_u32 v104, s69, v108
	v_mov_b32_e32 v105, v0
	v_lshl_add_u64 v[166:167], v[104:105], 1, v[102:103]
	s_lshl_b32 s2, s69, 3
	v_add_u32_e32 v104, s2, v104
	v_lshl_add_u64 v[168:169], v[104:105], 1, v[102:103]
	v_add_u32_e32 v98, 8, v108
	v_lshlrev_b32_e32 v99, 7, v98
	v_lshrrev_b32_e32 v98, 2, v98
	v_xor_b32_e32 v98, v98, v142
	v_lshlrev_b32_e32 v98, 4, v98
	v_and_b32_e32 v98, 0x70, v98
	v_add3_u32 v98, s53, v99, v98
	ds_read_b128 v[154:157], v98
	v_add_u32_e32 v104, s2, v104
	s_nop 1
	v_add_u32_e32 v98, 16, v108
	v_lshlrev_b32_e32 v99, 7, v98
	v_lshrrev_b32_e32 v98, 2, v98
	v_xor_b32_e32 v98, v98, v142
	v_lshlrev_b32_e32 v98, 4, v98
	v_and_b32_e32 v98, 0x70, v98
	v_add3_u32 v98, s53, v99, v98
	ds_read_b128 v[158:161], v98
	v_lshl_add_u64 v[170:171], v[104:105], 1, v[102:103]
	v_add_u32_e32 v104, s2, v104
	v_lshl_add_u64 v[172:173], v[104:105], 1, v[102:103]
	s_nop 1
	v_add_u32_e32 v98, 24, v108
	v_lshlrev_b32_e32 v99, 7, v98
	v_lshrrev_b32_e32 v98, 2, v98
	v_xor_b32_e32 v98, v98, v142
	v_lshlrev_b32_e32 v98, 4, v98
	v_and_b32_e32 v98, 0x70, v98
	v_add3_u32 v98, s53, v99, v98
	ds_read_b128 v[162:165], v98
	s_waitcnt lgkmcnt(3)
	global_store_dwordx4 v[166:167], v[150:153], off nt
	s_waitcnt lgkmcnt(2)
	global_store_dwordx4 v[168:169], v[154:157], off nt
	s_waitcnt lgkmcnt(1)
	global_store_dwordx4 v[170:171], v[158:161], off nt
	s_waitcnt lgkmcnt(0)
	global_store_dwordx4 v[172:173], v[162:165], off nt
	s_waitcnt lgkmcnt(0)
	s_barrier

.LBB0_336:
	v_and_b32_e32 v103, s24, v101
	v_lshlrev_b32_e32 v104, 4, v103
	v_ashrrev_i32_e32 v103, 4, v99
	v_add_u32_e32 v114, s75, v103
	v_xor_b32_e32 v103, v103, v101
	v_mov_b32_e32 v105, v0
	v_lshlrev_b32_e32 v103, 4, v103
	v_lshl_add_u64 v[108:109], s[48:49], 0, v[104:105]
	v_lshlrev_b32_e32 v104, 8, v114
	v_and_b32_e32 v103, 0xf0, v103
	s_waitcnt lgkmcnt(0)
	s_barrier
	v_add3_u32 v103, s53, v103, v104
	ds_read_b128 v[150:153], v103
	v_mul_lo_u32 v110, s5, v114
	v_mov_b32_e32 v111, v0
	v_lshl_add_u64 v[166:167], v[110:111], 1, v[108:109]
	v_add_u32_e32 v103, 4, v114
	s_lshl_b32 s5, s5, 2
	v_add_u32_e32 v110, s5, v110
	v_lshlrev_b32_e32 v104, 8, v103
	v_xor_b32_e32 v103, v103, v101
	v_lshlrev_b32_e32 v103, 4, v103
	v_and_b32_e32 v103, 0xf0, v103
	v_add3_u32 v103, s53, v103, v104
	ds_read_b128 v[154:157], v103
	v_lshl_add_u64 v[168:169], v[110:111], 1, v[108:109]
	v_add_u32_e32 v103, 8, v114
	v_add_u32_e32 v110, s5, v110
	v_lshl_add_u64 v[170:171], v[110:111], 1, v[108:109]
	s_nop 0
	v_lshlrev_b32_e32 v104, 8, v103
	v_xor_b32_e32 v103, v103, v101
	v_lshlrev_b32_e32 v103, 4, v103
	v_and_b32_e32 v103, 0xf0, v103
	v_add3_u32 v103, s53, v103, v104
	ds_read_b128 v[158:161], v103
	v_add_u32_e32 v103, 12, v114
	s_nop 1
	v_add_u32_e32 v104, s5, v110
	v_mov_b32_e32 v105, v0
	v_lshl_add_u64 v[172:173], v[104:105], 1, v[108:109]
	v_lshlrev_b32_e32 v104, 8, v103
	v_xor_b32_e32 v103, v103, v101
	v_lshlrev_b32_e32 v103, 4, v103
	v_and_b32_e32 v103, 0xf0, v103
	v_add3_u32 v103, s53, v103, v104
	ds_read_b128 v[162:165], v103
	s_waitcnt lgkmcnt(3)
	global_store_dwordx4 v[166:167], v[150:153], off nt
	s_waitcnt lgkmcnt(2)
	global_store_dwordx4 v[168:169], v[154:157], off nt
	s_waitcnt lgkmcnt(1)
	global_store_dwordx4 v[170:171], v[158:161], off nt
	s_waitcnt lgkmcnt(0)
	global_store_dwordx4 v[172:173], v[162:165], off nt
	s_waitcnt lgkmcnt(0)
	s_barrier
	s_cmp_lt_i32 s50, 8
	s_cbranch_scc0 .LBB0_307

.LBB0_352:
	v_lshlrev_b32_e32 v66, 4, v101
	v_ashrrev_i32_e32 v68, 3, v99
	v_and_b32_e32 v66, 0x70, v66
	v_mov_b32_e32 v67, v0
	v_lshl_add_u64 v[70:71], s[48:49], 0, v[66:67]
	v_lshrrev_b32_e32 v67, 2, v68
	v_xor_b32_e32 v67, v67, v101
	v_add_u32_e32 v76, s52, v68
	v_lshlrev_b32_e32 v67, 4, v67
	v_lshlrev_b32_e32 v66, 7, v76
	v_and_b32_e32 v67, 0x70, v67
	s_waitcnt lgkmcnt(0)
	s_barrier
	v_add3_u32 v66, s53, v66, v67
	ds_read_b128 v[150:153], v66
	v_mul_lo_u32 v72, s5, v76
	v_mov_b32_e32 v73, v0
	v_lshl_add_u64 v[166:167], v[72:73], 1, v[70:71]
	s_lshl_b32 s5, s5, 3
	v_add_u32_e32 v72, s5, v72
	v_lshl_add_u64 v[168:169], v[72:73], 1, v[70:71]
	v_add_u32_e32 v66, 8, v76
	v_lshlrev_b32_e32 v67, 7, v66
	v_lshrrev_b32_e32 v66, 2, v66
	v_xor_b32_e32 v66, v66, v101
	v_lshlrev_b32_e32 v66, 4, v66
	v_and_b32_e32 v66, 0x70, v66
	v_add3_u32 v66, s53, v67, v66
	ds_read_b128 v[154:157], v66
	v_add_u32_e32 v72, s5, v72
	s_nop 1
	v_add_u32_e32 v66, 16, v76
	v_lshlrev_b32_e32 v67, 7, v66
	v_lshrrev_b32_e32 v66, 2, v66
	v_xor_b32_e32 v66, v66, v101
	v_lshlrev_b32_e32 v66, 4, v66
	v_and_b32_e32 v66, 0x70, v66
	v_add3_u32 v66, s53, v67, v66
	ds_read_b128 v[158:161], v66
	v_lshl_add_u64 v[170:171], v[72:73], 1, v[70:71]
	v_add_u32_e32 v72, s5, v72
	v_lshl_add_u64 v[172:173], v[72:73], 1, v[70:71]
	s_nop 1
	v_add_u32_e32 v66, 24, v76
	v_lshlrev_b32_e32 v67, 7, v66
	v_lshrrev_b32_e32 v66, 2, v66
	v_xor_b32_e32 v66, v66, v101
	v_lshlrev_b32_e32 v66, 4, v66
	v_and_b32_e32 v66, 0x70, v66
	v_add3_u32 v66, s53, v67, v66
	ds_read_b128 v[162:165], v66
	s_waitcnt lgkmcnt(3)
	global_store_dwordx4 v[166:167], v[150:153], off nt
	s_waitcnt lgkmcnt(2)
	global_store_dwordx4 v[168:169], v[154:157], off nt
	s_waitcnt lgkmcnt(1)
	global_store_dwordx4 v[170:171], v[158:161], off nt
	s_waitcnt lgkmcnt(0)
	global_store_dwordx4 v[172:173], v[162:165], off nt
	s_waitcnt lgkmcnt(0)
	s_barrier
.LBB0_353:
	s_add_i32 s46, s17, 0x80
	s_lshl_b32 s5, s46, 7
	s_add_i32 s19, s5, 0xffc00000
	v_mov_b32_e32 v78, v1
	v_mov_b32_e32 v79, v249
	s_and_b64 s[48:49], s[10:11], exec
	s_cselect_b32 s24, s19, s5
	v_lshlrev_b32_e32 v66, 2, v79
	v_add_u32_e32 v68, s52, v66
	s_mov_b64 s[48:49], -1
	s_and_b64 vcc, exec, s[60:61]
	v_readlane_b32 s86, v251, 14
	s_cbranch_vccz .LBB0_380
	s_and_b64 vcc, exec, s[0:1]
	s_cbranch_vccnz .LBB0_379
	s_lshl_b32 s5, s46, 6
	s_add_i32 s19, s5, 0xffe00000
	s_mov_b32 s47, s75
	s_and_b64 s[0:1], s[10:11], exec
	v_readlane_b32 s72, v251, 3
	s_cselect_b32 s0, s19, s5
	s_lshl_b32 s48, s46, 3
	v_readlane_b32 s78, v251, 9
	v_readlane_b32 s5, v251, 37
	s_mov_b32 s1, s25
	v_readlane_b32 s79, v251, 10
	s_add_u32 s5, s78, s5
	s_addc_u32 s19, s79, 0
	s_lshl_b64 s[0:1], s[0:1], 2
	s_mov_b32 s49, s25
	s_add_u32 s0, s5, s0
	s_addc_u32 s1, s19, s1
	s_lshl_b64 s[48:49], s[48:49], 2
	v_readlane_b32 s36, v252, 47
	v_readlane_b32 s37, v252, 48
	s_add_u32 s82, s36, s48
	s_addc_u32 s83, s37, s49
	v_readlane_b32 s36, v251, 39
	v_readlane_b32 s73, v251, 4
	v_cmp_gt_i32_e32 vcc, 2, v79
	v_readlane_b32 s37, v251, 40
	v_ashrrev_i32_e32 v67, 31, v66
	s_and_b64 s[48:49], s[36:37], vcc
	v_lshlrev_b32_e32 v70, 3, v78
	v_lshl_add_u64 v[72:73], v[66:67], 2, s[82:83]
	s_mov_b64 s[72:73], -1
	s_and_b64 vcc, exec, s[66:67]
	v_readlane_b32 s74, v251, 5
	v_readlane_b32 s75, v251, 6
	v_readlane_b32 s76, v251, 7
	v_readlane_b32 s77, v251, 8
	s_cbranch_vccz .LBB0_359
	s_and_saveexec_b64 s[72:73], s[48:49]
	s_cbranch_execz .LBB0_358
	s_mov_b32 s36, 0x3d3504f3
	v_mov_b32_e32 v71, v0
	v_pk_mul_f32 v[76:77], v[12:13], s[36:37] op_sel_hi:[1,0]
	v_pk_mul_f32 v[74:75], v[10:11], s[36:37] op_sel_hi:[1,0]
	v_lshl_add_u64 v[80:81], v[70:71], 2, v[72:73]
	global_store_dwordx4 v[80:81], v[74:77], off nt

.LBB0_361:
	v_cndmask_b32_e64 v67, 0, 1, s[66:67]
	v_cmp_ne_u32_e64 s[0:1], 1, v67
	s_andn2_b64 vcc, exec, s[66:67]
	s_mov_b64 s[66:67], -1
	s_mov_b32 s74, 0xc2fc0000
	s_mov_b32 s75, s47
	s_cbranch_vccnz .LBB0_373
	s_and_saveexec_b64 s[66:67], s[48:49]
	s_cbranch_execz .LBB0_364
	s_mov_b32 s36, 0x3d3504f3
	v_add_u32_e32 v84, 0x80, v70
	v_mov_b32_e32 v85, v0
	v_pk_mul_f32 v[82:83], v[24:25], s[36:37] op_sel_hi:[1,0]
	v_pk_mul_f32 v[80:81], v[22:23], s[36:37] op_sel_hi:[1,0]
	v_lshl_add_u64 v[84:85], v[84:85], 2, v[72:73]
	global_store_dwordx4 v[84:85], v[80:83], off nt

.LBB0_366:
	s_and_saveexec_b64 s[66:67], s[48:49]
	s_cbranch_execz .LBB0_368
	s_mov_b32 s36, 0x3d3504f3
	v_add_u32_e32 v84, 0x100, v70
	v_mov_b32_e32 v85, v0
	v_pk_mul_f32 v[82:83], v[44:45], s[36:37] op_sel_hi:[1,0]
	v_pk_mul_f32 v[80:81], v[42:43], s[36:37] op_sel_hi:[1,0]
	v_lshl_add_u64 v[84:85], v[84:85], 2, v[72:73]
	global_store_dwordx4 v[84:85], v[80:83], off nt

.LBB0_370:
	s_and_saveexec_b64 s[0:1], s[48:49]
	s_cbranch_execz .LBB0_372
	s_mov_b32 s36, 0x3d3504f3
	v_add_u32_e32 v70, 0x180, v70
	v_mov_b32_e32 v71, v0
	v_pk_mul_f32 v[82:83], v[56:57], s[36:37] op_sel_hi:[1,0]
	v_pk_mul_f32 v[80:81], v[54:55], s[36:37] op_sel_hi:[1,0]
	v_lshl_add_u64 v[70:71], v[70:71], 2, v[72:73]
	global_store_dwordx4 v[70:71], v[80:83], off nt

.LBB0_418:
	s_waitcnt lgkmcnt(0)
	s_barrier
	v_and_b32_e32 v70, 15, v78
	v_readlane_b32 s36, v251, 51
	v_cmp_gt_u32_e32 vcc, 8, v70
	v_readlane_b32 s37, v251, 52
	s_or_b64 s[58:59], s[36:37], vcc
	s_and_saveexec_b64 s[46:47], s[58:59]
	s_mov_b32 s74, 0xc2fc0000
	s_mov_b32 s75, s76
	s_cbranch_execz .LBB0_420
	v_lshrrev_b32_e32 v70, 3, v70
	v_mul_u32_u24_e32 v70, s57, v70
	v_and_b32_e32 v71, s54, v78
	v_lshlrev_b32_e32 v70, 1, v70
	v_lshl_or_b32 v70, v71, 4, v70
	v_mov_b32_e32 v71, v0
	v_lshl_add_u64 v[74:75], s[70:71], 0, v[70:71]
	v_ashrrev_i32_e32 v70, 4, v67
	v_add_u32_e32 v79, s75, v70
	v_xor_b32_e32 v70, v70, v78
	v_lshlrev_b32_e32 v70, 4, v70
	v_lshlrev_b32_e32 v71, 8, v79
	v_and_b32_e32 v70, 0xf0, v70
	v_add3_u32 v70, s53, v70, v71
	ds_read_b128 v[150:153], v70
	v_mul_lo_u32 v76, s51, v79
	v_mov_b32_e32 v77, v0
	v_lshl_add_u64 v[166:167], v[76:77], 1, v[74:75]
	s_lshl_b32 s19, s51, 2
	v_add_u32_e32 v76, s19, v76
	v_lshl_add_u64 v[168:169], v[76:77], 1, v[74:75]
	v_add_u32_e32 v70, 4, v79
	v_lshlrev_b32_e32 v71, 8, v70
	v_xor_b32_e32 v70, v70, v78
	v_lshlrev_b32_e32 v70, 4, v70
	v_and_b32_e32 v70, 0xf0, v70
	v_add3_u32 v70, s53, v70, v71
	ds_read_b128 v[154:157], v70
	v_add_u32_e32 v76, s19, v76
	s_nop 1
	v_add_u32_e32 v70, 8, v79
	v_lshlrev_b32_e32 v71, 8, v70
	v_xor_b32_e32 v70, v70, v78
	v_lshlrev_b32_e32 v70, 4, v70
	v_and_b32_e32 v70, 0xf0, v70
	v_add3_u32 v70, s53, v70, v71
	ds_read_b128 v[158:161], v70
	v_lshl_add_u64 v[170:171], v[76:77], 1, v[74:75]
	s_nop 1
	v_add_u32_e32 v72, 12, v79
	v_add_u32_e32 v70, s19, v76
	v_mov_b32_e32 v71, v0
	v_lshl_add_u64 v[172:173], v[70:71], 1, v[74:75]
	v_xor_b32_e32 v71, v72, v78
	v_lshlrev_b32_e32 v71, 4, v71
	v_lshlrev_b32_e32 v70, 8, v72
	v_and_b32_e32 v71, 0xf0, v71
	v_add3_u32 v70, s53, v71, v70
	ds_read_b128 v[162:165], v70
	s_waitcnt lgkmcnt(3)
	global_store_dwordx4 v[166:167], v[150:153], off nt
	s_waitcnt lgkmcnt(2)
	global_store_dwordx4 v[168:169], v[154:157], off nt
	s_waitcnt lgkmcnt(1)
	global_store_dwordx4 v[170:171], v[158:161], off nt
	s_waitcnt lgkmcnt(0)
	global_store_dwordx4 v[172:173], v[162:165], off nt

.LBB0_433:
	v_lshlrev_b32_e32 v10, 4, v78
	v_ashrrev_i32_e32 v12, 3, v67
	v_and_b32_e32 v10, 0x70, v10
	v_mov_b32_e32 v11, v0
	v_lshl_add_u64 v[22:23], s[6:7], 0, v[10:11]
	v_lshrrev_b32_e32 v11, 2, v12
	v_xor_b32_e32 v11, v11, v78
	v_add_u32_e32 v32, s52, v12
	v_lshlrev_b32_e32 v11, 4, v11
	v_lshlrev_b32_e32 v10, 7, v32
	v_and_b32_e32 v11, 0x70, v11
	s_waitcnt lgkmcnt(0)
	s_barrier
	v_add3_u32 v10, s53, v10, v11
	ds_read_b128 v[150:153], v10
	v_mul_lo_u32 v24, s5, v32
	v_mov_b32_e32 v25, v0
	v_lshl_add_u64 v[166:167], v[24:25], 1, v[22:23]
	s_lshl_b32 s5, s5, 3
	v_add_u32_e32 v24, s5, v24
	v_lshl_add_u64 v[168:169], v[24:25], 1, v[22:23]
	v_add_u32_e32 v10, 8, v32
	v_lshlrev_b32_e32 v11, 7, v10
	v_lshrrev_b32_e32 v10, 2, v10
	v_xor_b32_e32 v10, v10, v78
	v_lshlrev_b32_e32 v10, 4, v10
	v_and_b32_e32 v10, 0x70, v10
	v_add3_u32 v10, s53, v11, v10
	ds_read_b128 v[154:157], v10
	v_add_u32_e32 v24, s5, v24
	s_nop 1
	v_add_u32_e32 v10, 16, v32
	v_lshlrev_b32_e32 v11, 7, v10
	v_lshrrev_b32_e32 v10, 2, v10
	v_xor_b32_e32 v10, v10, v78
	v_lshlrev_b32_e32 v10, 4, v10
	v_and_b32_e32 v10, 0x70, v10
	v_add3_u32 v10, s53, v11, v10
	ds_read_b128 v[158:161], v10
	v_lshl_add_u64 v[170:171], v[24:25], 1, v[22:23]
	v_add_u32_e32 v24, s5, v24
	v_lshl_add_u64 v[172:173], v[24:25], 1, v[22:23]
	s_nop 1
	v_add_u32_e32 v10, 24, v32
	v_lshlrev_b32_e32 v11, 7, v10
	v_lshrrev_b32_e32 v10, 2, v10
	v_xor_b32_e32 v10, v10, v78
	v_lshlrev_b32_e32 v10, 4, v10
	v_and_b32_e32 v10, 0x70, v10
	v_add3_u32 v10, s53, v11, v10
	ds_read_b128 v[162:165], v10
	s_waitcnt lgkmcnt(3)
	global_store_dwordx4 v[166:167], v[150:153], off nt
	s_waitcnt lgkmcnt(2)
	global_store_dwordx4 v[168:169], v[154:157], off nt
	s_waitcnt lgkmcnt(1)
	global_store_dwordx4 v[170:171], v[158:161], off nt
	s_waitcnt lgkmcnt(0)
	global_store_dwordx4 v[172:173], v[162:165], off nt
	s_waitcnt lgkmcnt(0)
	s_barrier

.LBB0_467:
	v_and_b32_e32 v13, s5, v1
	v_lshlrev_b32_e32 v22, 4, v13
	v_ashrrev_i32_e32 v13, 4, v11
	v_add_u32_e32 v44, s75, v13
	v_xor_b32_e32 v13, v13, v1
	v_mov_b32_e32 v23, v0
	v_lshlrev_b32_e32 v13, 4, v13
	v_lshl_add_u64 v[30:31], s[2:3], 0, v[22:23]
	v_lshlrev_b32_e32 v22, 8, v44
	v_and_b32_e32 v13, 0xf0, v13
	s_waitcnt lgkmcnt(0)
	s_barrier
	v_add3_u32 v13, s53, v13, v22
	ds_read_b128 v[150:153], v13
	v_mul_lo_u32 v32, s4, v44
	v_mov_b32_e32 v33, v0
	v_lshl_add_u64 v[166:167], v[32:33], 1, v[30:31]
	v_add_u32_e32 v13, 4, v44
	s_lshl_b32 s2, s4, 2
	v_add_u32_e32 v32, s2, v32
	v_lshlrev_b32_e32 v22, 8, v13
	v_xor_b32_e32 v13, v13, v1
	v_lshlrev_b32_e32 v13, 4, v13
	v_and_b32_e32 v13, 0xf0, v13
	v_add3_u32 v13, s53, v13, v22
	ds_read_b128 v[154:157], v13
	v_lshl_add_u64 v[168:169], v[32:33], 1, v[30:31]
	v_add_u32_e32 v13, 8, v44
	v_add_u32_e32 v32, s2, v32
	v_lshl_add_u64 v[170:171], v[32:33], 1, v[30:31]
	s_nop 0
	v_lshlrev_b32_e32 v22, 8, v13
	v_xor_b32_e32 v13, v13, v1
	v_lshlrev_b32_e32 v13, 4, v13
	v_and_b32_e32 v13, 0xf0, v13
	v_add3_u32 v13, s53, v13, v22
	ds_read_b128 v[158:161], v13
	v_add_u32_e32 v13, 12, v44
	s_nop 1
	v_add_u32_e32 v22, s2, v32
	v_mov_b32_e32 v23, v0
	v_lshl_add_u64 v[172:173], v[22:23], 1, v[30:31]
	v_lshlrev_b32_e32 v22, 8, v13
	v_xor_b32_e32 v13, v13, v1
	v_lshlrev_b32_e32 v13, 4, v13
	v_and_b32_e32 v13, 0xf0, v13
	v_add3_u32 v13, s53, v13, v22
	ds_read_b128 v[162:165], v13
	s_waitcnt lgkmcnt(3)
	global_store_dwordx4 v[166:167], v[150:153], off nt
	s_waitcnt lgkmcnt(2)
	global_store_dwordx4 v[168:169], v[154:157], off nt
	s_waitcnt lgkmcnt(1)
	global_store_dwordx4 v[170:171], v[158:161], off nt
	s_waitcnt lgkmcnt(0)
	global_store_dwordx4 v[172:173], v[162:165], off nt
	s_waitcnt lgkmcnt(0)
	s_barrier
	s_cmp_lt_i32 s50, 8
	s_cbranch_scc0 .LBB0_438

.LBB0_691:
	s_or_b64 exec, exec, s[0:1]
	v_lshrrev_b32_e32 v200, 3, v67
	v_mul_u32_u24_e32 v201, v4, v200
	v_and_b32_e32 v202, 7, v67
	v_lshlrev_b32_e32 v201, 1, v201
	v_lshlrev_b32_e32 v202, 4, v202
	v_lshl_add_u32 v201, v6, 1, v201
	v_add_u32_e32 v202, v201, v202
	v_mov_b32_e32 v203, 0
	v_lshl_add_u64 v[204:205], v[0:1], 0, v[202:203]
	v_lshl_add_u64 v[206:207], v[2:3], 0, v[202:203]
	v_lshlrev_b32_e32 v208, 6, v4
	v_mov_b32_e32 v209, 0
	global_load_dwordx4 v[160:163], v[204:205], off nt
	global_load_dwordx4 v[176:179], v[206:207], off nt
	v_lshl_add_u64 v[204:205], v[204:205], 0, v[208:209]
	v_lshl_add_u64 v[206:207], v[206:207], 0, v[208:209]
	global_load_dwordx4 v[164:167], v[204:205], off nt
	global_load_dwordx4 v[180:183], v[206:207], off nt
	v_lshl_add_u64 v[204:205], v[204:205], 0, v[208:209]
	v_lshl_add_u64 v[206:207], v[206:207], 0, v[208:209]
	global_load_dwordx4 v[168:171], v[204:205], off nt
	global_load_dwordx4 v[184:187], v[206:207], off nt
	v_lshl_add_u64 v[204:205], v[204:205], 0, v[208:209]
	v_lshl_add_u64 v[206:207], v[206:207], 0, v[208:209]
	global_load_dwordx4 v[172:175], v[204:205], off nt
	global_load_dwordx4 v[188:191], v[206:207], off nt
	s_mul_i32 s99, s98, 0x9000
	v_mul_u32_u24_e32 v212, 0x14000, v150
	v_add_u32_e32 v212, s99, v212
	v_mul_u32_u24_e32 v210, 0x90, v200
	v_and_b32_e32 v211, 7, v67
	v_lshl_add_u32 v210, v211, 4, v210
	v_add_u32_e32 v210, v210, v212
	v_and_b32_e32 v213, 0x5f, v67
	v_mul_u32_u24_e32 v213, 0x90, v213
	v_bfe_u32 v211, v67, 5, 1
	v_lshl_add_u32 v213, v211, 4, v213
	v_add_u32_e32 v213, v213, v212
	v_ashrrev_i32_e32 v214, 1, v67
	v_and_b32_e32 v214, 0xffc0, v214
	v_and_b32_e32 v215, 31, v67
	v_or_b32_e32 v214, v214, v215
	v_mul_u32_u24_e32 v214, 0x90, v214
	v_lshl_add_u32 v214, v211, 4, v214
	v_add_u32_e32 v214, v214, v212
	v_add_u32_e32 v214, 0x4800, v214
	s_waitcnt vmcnt(0)
	ds_write_b128 v210, v[160:163]
	ds_write_b128 v210, v[164:167] offset:4608
	ds_write_b128 v210, v[168:171] offset:9216
	ds_write_b128 v210, v[172:175] offset:13824
	ds_write_b128 v210, v[176:179] offset:18432
	ds_write_b128 v210, v[180:183] offset:23040
	ds_write_b128 v210, v[184:187] offset:27648
	ds_write_b128 v210, v[188:191] offset:32256
	s_waitcnt lgkmcnt(0)
	s_barrier
	v_and_b32_e32 v18, 0x5f, v67
	v_and_b32_e32 v5, 31, v67
	v_ashrrev_i32_e32 v10, 1, v67
	v_mul_u32_u24_e32 v7, v4, v18
	v_lshlrev_b32_e32 v64, 1, v7
	v_and_or_b32 v102, v10, s3, v5
	v_bfe_u32 v71, v67, 5, 1
	v_lshl_add_u64 v[8:9], v[0:1], 0, v[64:65]
	v_lshlrev_b32_e32 v64, 1, v6
	v_or_b32_e32 v66, 32, v102
	v_lshl_add_u64 v[6:7], v[8:9], 0, v[64:65]
	v_lshlrev_b32_e32 v14, 4, v71
	v_mov_b32_e32 v15, v65
	v_mad_i64_i32 v[10:11], s[0:1], v4, v102, 0
	v_mad_i64_i32 v[16:17], s[0:1], v4, v66, 0
	v_lshl_add_u64 v[92:93], v[6:7], 0, v[14:15]
	v_lshl_add_u64 v[10:11], v[10:11], 1, v[2:3]
	v_lshl_add_u64 v[2:3], v[16:17], 1, v[2:3]
	ds_read_b128 v[6:9], v213
	v_lshl_add_u64 v[2:3], v[2:3], 0, v[64:65]
	v_lshl_add_u64 v[96:97], v[2:3], 0, v[14:15]
	v_or_b32_e32 v2, 32, v18
	v_lshl_add_u64 v[10:11], v[10:11], 0, v[64:65]
	v_mul_u32_u24_e32 v2, v4, v2
	v_lshl_add_u64 v[94:95], v[10:11], 0, v[14:15]
	v_mov_b32_e32 v3, v65
	v_lshlrev_b32_e32 v2, 1, v2
	ds_read_b128 v[10:13], v214
	ds_read_b128 v[72:75], v214 offset:4608
	v_lshl_add_u64 v[0:1], v[0:1], 0, v[2:3]
	v_lshl_add_u64 v[0:1], v[0:1], 0, v[64:65]
	v_lshl_add_u64 v[100:101], v[0:1], 0, v[14:15]
	ds_read_b128 v[76:79], v213 offset:32
	ds_read_b128 v[80:83], v214 offset:32
	ds_read_b128 v[0:3], v213 offset:4608
	ds_read_b128 v[84:87], v214 offset:4640
	ds_read_b128 v[88:91], v213 offset:4640
	v_lshlrev_b32_e32 v64, 7, v67
	v_and_b32_e32 v64, 0x2000, v64
	v_ashrrev_i32_e32 v69, 31, v68
	v_lshl_or_b32 v64, v71, 9, v64
	v_lshlrev_b64 v[68:69], 15, v[68:69]
	v_or_b32_e32 v71, 0x800, v64
	v_or_b32_e32 v103, 0x880, v64
	v_or_b32_e32 v104, 0x900, v64
	v_or_b32_e32 v105, 0x980, v64
	v_or_b32_e32 v106, 0xc00, v64
	v_or_b32_e32 v107, 0xc80, v64
	v_lshl_add_u64 v[68:69], s[88:89], 0, v[68:69]
	v_ashrrev_i32_e32 v67, 31, v66
	v_add_u32_e32 v70, 0x8000, v70
	s_waitcnt lgkmcnt(6)
	v_mfma_f32_32x32x16_bf16 v[48:63], v[6:9], v[10:13], 0
	s_waitcnt lgkmcnt(5)
	v_mfma_f32_32x32x16_bf16 v[32:47], v[6:9], v[72:75], 0
	s_waitcnt lgkmcnt(2)
	v_mfma_f32_32x32x16_bf16 v[16:31], v[0:3], v[10:13], 0
	v_mfma_f32_32x32x16_bf16 v[0:15], v[0:3], v[72:75], 0
	ds_read_b128 v[72:75], v213 offset:64
	v_mfma_f32_32x32x16_bf16 v[48:63], v[76:79], v[80:83], v[48:63]
	s_waitcnt lgkmcnt(2)
	v_mfma_f32_32x32x16_bf16 v[32:47], v[76:79], v[84:87], v[32:47]
	ds_read_b128 v[76:79], v214 offset:64
	s_waitcnt lgkmcnt(2)
	v_mfma_f32_32x32x16_bf16 v[16:31], v[88:91], v[80:83], v[16:31]
	v_mfma_f32_32x32x16_bf16 v[0:15], v[88:91], v[84:87], v[0:15]
	ds_read_b128 v[80:83], v214 offset:4672
	ds_read_b128 v[84:87], v213 offset:96
	ds_read_b128 v[88:91], v214 offset:96
	s_nop 0
	ds_read_b128 v[92:95], v213 offset:4672
	s_nop 0
	ds_read_b128 v[96:99], v214 offset:4704
	s_waitcnt lgkmcnt(4)
	v_mfma_f32_32x32x16_bf16 v[32:47], v[72:75], v[80:83], v[32:47]
	v_mfma_f32_32x32x16_bf16 v[48:63], v[72:75], v[76:79], v[48:63]
	ds_read_b128 v[72:75], v213 offset:4704
	v_add_u32_e32 v100, v107, v102
	v_ashrrev_i32_e32 v101, 31, v100
	s_waitcnt lgkmcnt(3)
	v_mfma_f32_32x32x16_bf16 v[48:63], v[84:87], v[88:91], v[48:63]
	s_waitcnt lgkmcnt(2)
	v_mfma_f32_32x32x16_bf16 v[16:31], v[92:95], v[76:79], v[16:31]
	v_mfma_f32_32x32x16_bf16 v[0:15], v[92:95], v[80:83], v[0:15]
	s_waitcnt lgkmcnt(1)
	v_mfma_f32_32x32x16_bf16 v[32:47], v[84:87], v[96:99], v[32:47]
	s_waitcnt lgkmcnt(0)
	v_mfma_f32_32x32x16_bf16 v[16:31], v[72:75], v[88:91], v[16:31]
	v_mfma_f32_32x32x16_bf16 v[0:15], v[72:75], v[96:99], v[0:15]
	v_and_b32_e32 v216, 63, v151
	v_lshrrev_b32_e32 v217, 6, v151
	v_and_b32_e32 v218, 31, v216
	v_lshrrev_b32_e32 v219, 5, v216
	v_mul_u32_u24_e32 v220, 0x14000, v150
	v_lshl_add_u32 v220, v217, 11, v220
	v_add_u32_e32 v220, 0x12000, v220
	v_lshlrev_b32_e32 v221, 9, v219
	v_lshl_add_u32 v221, v218, 1, v221
	v_add_u32_e32 v221, v221, v220
	v_lshl_add_u32 v222, v216, 4, v220
	v_and_b32_e32 v224, 1, v217
	v_lshlrev_b32_e32 v224, 6, v224
	v_lshrrev_b32_e32 v223, 3, v216
	v_add_u32_e32 v224, v224, v223
	v_lshlrev_b32_e32 v224, 8, v224
	v_lshrrev_b32_e32 v223, 1, v217
	v_lshl_add_u32 v224, v223, 7, v224
	v_and_b32_e32 v223, 7, v216
	v_lshl_add_u32 v224, v223, 4, v224
	v_mov_b32_e32 v225, 0
	v_lshl_add_u64 v[226:227], v[68:69], 0, v[224:225]
	v_mov_b32_e32 v208, 0x800
	v_mov_b32_e32 v209, 0
	s_nop 7
	v_cvt_pk_bf16_f32 v176, v48, s0
	ds_write_b16 v221, v176
	v_cvt_pk_bf16_f32 v177, v49, s0
	ds_write_b16 v221, v177 offset:128
	v_cvt_pk_bf16_f32 v178, v50, s0
	ds_write_b16 v221, v178 offset:256
	v_cvt_pk_bf16_f32 v179, v51, s0
	ds_write_b16 v221, v179 offset:384
	v_cvt_pk_bf16_f32 v180, v32, s0
	ds_write_b16 v221, v180 offset:64
	v_cvt_pk_bf16_f32 v181, v33, s0
	ds_write_b16 v221, v181 offset:192
	v_cvt_pk_bf16_f32 v182, v34, s0
	ds_write_b16 v221, v182 offset:320
	v_cvt_pk_bf16_f32 v183, v35, s0
	ds_write_b16 v221, v183 offset:448
	s_waitcnt lgkmcnt(0)
	ds_read_b128 v[200:203], v222
	v_cvt_pk_bf16_f32 v176, v52, s0
	ds_write_b16 v221, v176 offset:1024
	v_cvt_pk_bf16_f32 v177, v53, s0
	ds_write_b16 v221, v177 offset:1152
	v_cvt_pk_bf16_f32 v178, v54, s0
	ds_write_b16 v221, v178 offset:1280
	v_cvt_pk_bf16_f32 v179, v55, s0
	ds_write_b16 v221, v179 offset:1408
	v_cvt_pk_bf16_f32 v180, v36, s0
	ds_write_b16 v221, v180 offset:1088
	v_cvt_pk_bf16_f32 v181, v37, s0
	ds_write_b16 v221, v181 offset:1216
	v_cvt_pk_bf16_f32 v182, v38, s0
	ds_write_b16 v221, v182 offset:1344
	v_cvt_pk_bf16_f32 v183, v39, s0
	ds_write_b16 v221, v183 offset:1472
	s_waitcnt lgkmcnt(0)
	ds_read_b128 v[204:207], v222 offset:1024
	global_store_dwordx4 v[226:227], v[200:203], off nt
	v_lshl_add_u64 v[226:227], v[226:227], 0, v[208:209]
	v_cvt_pk_bf16_f32 v176, v56, s0
	ds_write_b16 v221, v176
	v_cvt_pk_bf16_f32 v177, v57, s0
	ds_write_b16 v221, v177 offset:128
	v_cvt_pk_bf16_f32 v178, v58, s0
	ds_write_b16 v221, v178 offset:256
	v_cvt_pk_bf16_f32 v179, v59, s0
	ds_write_b16 v221, v179 offset:384
	v_cvt_pk_bf16_f32 v180, v40, s0
	ds_write_b16 v221, v180 offset:64
	v_cvt_pk_bf16_f32 v181, v41, s0
	ds_write_b16 v221, v181 offset:192
	v_cvt_pk_bf16_f32 v182, v42, s0
	ds_write_b16 v221, v182 offset:320
	v_cvt_pk_bf16_f32 v183, v43, s0
	ds_write_b16 v221, v183 offset:448
	s_waitcnt lgkmcnt(0)
	ds_read_b128 v[200:203], v222
	global_store_dwordx4 v[226:227], v[204:207], off nt
	v_lshl_add_u64 v[226:227], v[226:227], 0, v[208:209]
	v_cvt_pk_bf16_f32 v176, v60, s0
	ds_write_b16 v221, v176 offset:1024
	v_cvt_pk_bf16_f32 v177, v61, s0
	ds_write_b16 v221, v177 offset:1152
	v_cvt_pk_bf16_f32 v178, v62, s0
	ds_write_b16 v221, v178 offset:1280
	v_cvt_pk_bf16_f32 v179, v63, s0
	ds_write_b16 v221, v179 offset:1408
	v_cvt_pk_bf16_f32 v180, v44, s0
	ds_write_b16 v221, v180 offset:1088
	v_cvt_pk_bf16_f32 v181, v45, s0
	ds_write_b16 v221, v181 offset:1216
	v_cvt_pk_bf16_f32 v182, v46, s0
	ds_write_b16 v221, v182 offset:1344
	v_cvt_pk_bf16_f32 v183, v47, s0
	ds_write_b16 v221, v183 offset:1472
	s_waitcnt lgkmcnt(0)
	ds_read_b128 v[204:207], v222 offset:1024
	global_store_dwordx4 v[226:227], v[200:203], off nt
	v_lshl_add_u64 v[226:227], v[226:227], 0, v[208:209]
	v_cvt_pk_bf16_f32 v176, v16, s0
	ds_write_b16 v221, v176
	v_cvt_pk_bf16_f32 v177, v17, s0
	ds_write_b16 v221, v177 offset:128
	v_cvt_pk_bf16_f32 v178, v18, s0
	ds_write_b16 v221, v178 offset:256
	v_cvt_pk_bf16_f32 v179, v19, s0
	ds_write_b16 v221, v179 offset:384
	v_cvt_pk_bf16_f32 v180, v0, s0
	ds_write_b16 v221, v180 offset:64
	v_cvt_pk_bf16_f32 v181, v1, s0
	ds_write_b16 v221, v181 offset:192
	v_cvt_pk_bf16_f32 v182, v2, s0
	ds_write_b16 v221, v182 offset:320
	v_cvt_pk_bf16_f32 v183, v3, s0
	ds_write_b16 v221, v183 offset:448
	s_waitcnt lgkmcnt(0)
	ds_read_b128 v[200:203], v222
	global_store_dwordx4 v[226:227], v[204:207], off nt
	v_lshl_add_u64 v[226:227], v[226:227], 0, v[208:209]
	v_cvt_pk_bf16_f32 v176, v20, s0
	ds_write_b16 v221, v176 offset:1024
	v_cvt_pk_bf16_f32 v177, v21, s0
	ds_write_b16 v221, v177 offset:1152
	v_cvt_pk_bf16_f32 v178, v22, s0
	ds_write_b16 v221, v178 offset:1280
	v_cvt_pk_bf16_f32 v179, v23, s0
	ds_write_b16 v221, v179 offset:1408
	v_cvt_pk_bf16_f32 v180, v4, s0
	ds_write_b16 v221, v180 offset:1088
	v_cvt_pk_bf16_f32 v181, v5, s0
	ds_write_b16 v221, v181 offset:1216
	v_cvt_pk_bf16_f32 v182, v6, s0
	ds_write_b16 v221, v182 offset:1344
	v_cvt_pk_bf16_f32 v183, v7, s0
	ds_write_b16 v221, v183 offset:1472
	s_waitcnt lgkmcnt(0)
	ds_read_b128 v[204:207], v222 offset:1024
	global_store_dwordx4 v[226:227], v[200:203], off nt
	v_lshl_add_u64 v[226:227], v[226:227], 0, v[208:209]
	v_cvt_pk_bf16_f32 v176, v24, s0
	ds_write_b16 v221, v176
	v_cvt_pk_bf16_f32 v177, v25, s0
	ds_write_b16 v221, v177 offset:128
	v_cvt_pk_bf16_f32 v178, v26, s0
	ds_write_b16 v221, v178 offset:256
	v_cvt_pk_bf16_f32 v179, v27, s0
	ds_write_b16 v221, v179 offset:384
	v_cvt_pk_bf16_f32 v180, v8, s0
	ds_write_b16 v221, v180 offset:64
	v_cvt_pk_bf16_f32 v181, v9, s0
	ds_write_b16 v221, v181 offset:192
	v_cvt_pk_bf16_f32 v182, v10, s0
	ds_write_b16 v221, v182 offset:320
	v_cvt_pk_bf16_f32 v183, v11, s0
	ds_write_b16 v221, v183 offset:448
	s_waitcnt lgkmcnt(0)
	ds_read_b128 v[200:203], v222
	global_store_dwordx4 v[226:227], v[204:207], off nt
	v_lshl_add_u64 v[226:227], v[226:227], 0, v[208:209]
	v_cvt_pk_bf16_f32 v176, v28, s0
	ds_write_b16 v221, v176 offset:1024
	v_cvt_pk_bf16_f32 v177, v29, s0
	ds_write_b16 v221, v177 offset:1152
	v_cvt_pk_bf16_f32 v178, v30, s0
	ds_write_b16 v221, v178 offset:1280
	v_cvt_pk_bf16_f32 v179, v31, s0
	ds_write_b16 v221, v179 offset:1408
	v_cvt_pk_bf16_f32 v180, v12, s0
	ds_write_b16 v221, v180 offset:1088
	v_cvt_pk_bf16_f32 v181, v13, s0
	ds_write_b16 v221, v181 offset:1216
	v_cvt_pk_bf16_f32 v182, v14, s0
	ds_write_b16 v221, v182 offset:1344
	v_cvt_pk_bf16_f32 v183, v15, s0
	ds_write_b16 v221, v183 offset:1472
	s_waitcnt lgkmcnt(0)
	ds_read_b128 v[204:207], v222 offset:1024
	global_store_dwordx4 v[226:227], v[200:203], off nt
	v_lshl_add_u64 v[226:227], v[226:227], 0, v[208:209]
	s_waitcnt lgkmcnt(0)
	global_store_dwordx4 v[226:227], v[204:207], off nt
	s_add_i32 s0, s4, 0x200
	s_xor_b32 s98, s98, 1
	s_cmpk_gt_i32 s4, 0x61f
	s_mov_b32 s4, s0
	s_cbranch_scc1 .LBB0_696

.LBB0_759:
	s_or_b64 exec, exec, s[14:15]
	v_lshrrev_b32_e32 v216, 6, v140
	v_mul_u32_u24_e32 v216, 0x1200, v216
	v_add_u32_e32 v216, v216, v141
	v_add_u32_e32 v216, 0x3000, v216
	v_lshrrev_b32_e32 v220, 3, v198
	v_and_b32_e32 v221, 7, v198
	v_mul_u32_u24_e32 v217, 0x90, v220
	v_lshl_add_u32 v217, v221, 4, v217
	v_add_u32_e32 v217, v217, v216
	v_lshrrev_b32_e32 v220, 4, v198
	v_and_b32_e32 v221, 15, v198
	v_mul_u32_u24_e32 v222, 0x90, v220
	v_lshl_add_u32 v222, v221, 3, v222
	v_add_u32_e32 v222, v222, v216
	v_and_b32_e32 v218, 31, v198
	v_lshrrev_b32_e32 v219, 5, v198
	v_mul_u32_u24_e32 v223, 0x90, v218
	v_lshl_add_u32 v223, v219, 3, v223
	v_add_u32_e32 v216, v223, v216
	ds_write_b128 v217, v[112:115]
	ds_write_b128 v217, v[116:119] offset:1152
	ds_write_b128 v217, v[120:123] offset:2304
	ds_write_b64 v222, v[124:125] offset:3456
	ds_write_b64 v222, v[128:129] offset:4032
	s_waitcnt lgkmcnt(0)
	ds_read_b64 v[128:129], v216
	ds_read_b64 v[124:125], v216 offset:16
	ds_read_b64 v[122:123], v216 offset:32
	ds_read_b64 v[120:121], v216 offset:48
	ds_read_b64 v[118:119], v216 offset:64
	ds_read_b64 v[116:117], v216 offset:80
	ds_read_b64 v[114:115], v216 offset:96
	ds_read_b64 v[112:113], v216 offset:112
	s_waitcnt lgkmcnt(0)
	ds_bpermute_b32 v4, v234, v10
	v_and_b32_e32 v5, 0xffff0000, v128
	v_lshl_add_u64 v[2:3], v[126:127], 1, v[130:131]
	v_lshl_add_u64 v[2:3], v[2:3], 0, v[0:1]
	s_waitcnt lgkmcnt(0)
	v_add_f32_e32 v4, v10, v4
	v_max_f32_e32 v6, 0xda24260, v4
	v_div_scale_f32 v7, s[14:15], v6, v6, 1.0
	v_rcp_f32_e32 v8, v7
	v_div_scale_f32 v9, vcc, 1.0, v6, 1.0
	v_lshlrev_b32_e32 v4, 16, v128
	v_fma_f32 v10, -v7, v8, 1.0
	v_fmac_f32_e32 v8, v10, v8
	v_mul_f32_e32 v10, v9, v8
	v_fma_f32 v11, -v7, v10, v9
	v_fmac_f32_e32 v10, v11, v8
	v_fma_f32 v7, -v7, v10, v9
	v_div_fmas_f32 v7, v7, v8, v10
	v_div_fixup_f32 v6, v7, v6, 1.0
	v_pk_mul_f32 v[8:9], v[32:33], v[6:7] op_sel_hi:[1,0]
	v_pk_mul_f32 v[10:11], v[34:35], v[6:7] op_sel_hi:[1,0]
	v_pk_mul_f32 v[4:5], v[8:9], v[4:5]
	v_and_b32_e32 v9, 0xffff0000, v129
	v_lshlrev_b32_e32 v8, 16, v129
	v_pk_mul_f32 v[8:9], v[10:11], v[8:9]
	s_mov_b64 s[14:15], 0x16f80400
	v_cvt_pk_bf16_f32 v4, v4, v5
	v_cvt_pk_bf16_f32 v5, v8, v9
	v_lshl_add_u64 v[8:9], v[2:3], 0, s[14:15]
	s_mov_b32 s14, 0x16f80000
	v_add_co_u32_e32 v2, vcc, s14, v2
	v_pk_mul_f32 v[10:11], v[38:39], v[6:7] op_sel_hi:[1,0]
	s_nop 0
	v_addc_co_u32_e32 v3, vcc, 0, v3, vcc
	v_lshrrev_b32_e32 v216, 6, v140
	v_mul_u32_u24_e32 v216, 0x1200, v216
	v_add_u32_e32 v216, v216, v141
	v_add_u32_e32 v216, 0x3000, v216
	v_and_b32_e32 v218, 31, v198
	v_lshrrev_b32_e32 v219, 5, v198
	v_lshrrev_b32_e32 v220, 3, v198
	v_and_b32_e32 v221, 7, v198
	v_mul_u32_u24_e32 v222, 0x90, v220
	v_lshl_add_u32 v222, v221, 4, v222
	v_add_u32_e32 v217, v222, v216
	v_mul_u32_u24_e32 v222, 0x90, v218
	v_lshl_add_u32 v222, v219, 3, v222
	v_add_u32_e32 v216, v222, v216
	v_sub_u32_e32 v220, v220, v218
	v_lshlrev_b32_e32 v220, 11, v220
	v_lshl_add_u32 v220, v221, 4, v220
	v_lshlrev_b32_e32 v219, 3, v219
	v_sub_u32_e32 v220, v220, v219
	v_ashrrev_i32_e32 v221, 31, v220
	v_lshl_add_u64 v[218:219], v[8:9], 0, v[220:221]
	ds_write_b64 v216, v[4:5]
	v_and_b32_e32 v3, 0xffff0000, v124
	v_lshlrev_b32_e32 v2, 16, v124
	v_pk_mul_f32 v[4:5], v[36:37], v[6:7] op_sel_hi:[1,0]
	s_nop 0
	v_pk_mul_f32 v[2:3], v[4:5], v[2:3]
	v_and_b32_e32 v5, 0xffff0000, v125
	v_lshlrev_b32_e32 v4, 16, v125
	v_pk_mul_f32 v[4:5], v[10:11], v[4:5]
	v_cvt_pk_bf16_f32 v2, v2, v3
	v_cvt_pk_bf16_f32 v3, v4, v5
	ds_write_b64 v216, v[2:3] offset:16
	v_and_b32_e32 v3, 0xffff0000, v122
	v_lshlrev_b32_e32 v2, 16, v122
	v_pk_mul_f32 v[4:5], v[40:41], v[6:7] op_sel_hi:[1,0]
	v_pk_mul_f32 v[10:11], v[42:43], v[6:7] op_sel_hi:[1,0]
	v_pk_mul_f32 v[2:3], v[4:5], v[2:3]
	v_and_b32_e32 v5, 0xffff0000, v123
	v_lshlrev_b32_e32 v4, 16, v123
	v_pk_mul_f32 v[4:5], v[10:11], v[4:5]
	v_cvt_pk_bf16_f32 v2, v2, v3
	v_cvt_pk_bf16_f32 v3, v4, v5
	ds_write_b64 v216, v[2:3] offset:32
	v_and_b32_e32 v3, 0xffff0000, v120
	v_lshlrev_b32_e32 v2, 16, v120
	v_pk_mul_f32 v[4:5], v[44:45], v[6:7] op_sel_hi:[1,0]
	v_pk_mul_f32 v[10:11], v[46:47], v[6:7] op_sel_hi:[1,0]
	v_pk_mul_f32 v[2:3], v[4:5], v[2:3]
	v_and_b32_e32 v5, 0xffff0000, v121
	v_lshlrev_b32_e32 v4, 16, v121
	v_pk_mul_f32 v[4:5], v[10:11], v[4:5]
	v_cvt_pk_bf16_f32 v2, v2, v3
	v_cvt_pk_bf16_f32 v3, v4, v5
	ds_write_b64 v216, v[2:3] offset:48
	v_and_b32_e32 v3, 0xffff0000, v118
	v_lshlrev_b32_e32 v2, 16, v118
	v_pk_mul_f32 v[4:5], v[16:17], v[6:7] op_sel_hi:[1,0]
	v_pk_mul_f32 v[10:11], v[18:19], v[6:7] op_sel_hi:[1,0]
	v_pk_mul_f32 v[2:3], v[4:5], v[2:3]
	v_and_b32_e32 v5, 0xffff0000, v119
	v_lshlrev_b32_e32 v4, 16, v119
	v_pk_mul_f32 v[4:5], v[10:11], v[4:5]
	v_cvt_pk_bf16_f32 v2, v2, v3
	v_cvt_pk_bf16_f32 v3, v4, v5
	ds_write_b64 v216, v[2:3] offset:64
	v_and_b32_e32 v3, 0xffff0000, v116
	v_lshlrev_b32_e32 v2, 16, v116
	v_pk_mul_f32 v[4:5], v[20:21], v[6:7] op_sel_hi:[1,0]
	v_pk_mul_f32 v[10:11], v[22:23], v[6:7] op_sel_hi:[1,0]
	v_pk_mul_f32 v[2:3], v[4:5], v[2:3]
	v_and_b32_e32 v5, 0xffff0000, v117
	v_lshlrev_b32_e32 v4, 16, v117
	v_pk_mul_f32 v[4:5], v[10:11], v[4:5]
	v_cvt_pk_bf16_f32 v2, v2, v3
	v_cvt_pk_bf16_f32 v3, v4, v5
	ds_write_b64 v216, v[2:3] offset:80
	v_and_b32_e32 v3, 0xffff0000, v114
	v_lshlrev_b32_e32 v2, 16, v114
	v_pk_mul_f32 v[4:5], v[24:25], v[6:7] op_sel_hi:[1,0]
	v_pk_mul_f32 v[10:11], v[26:27], v[6:7] op_sel_hi:[1,0]
	v_pk_mul_f32 v[2:3], v[4:5], v[2:3]
	v_and_b32_e32 v5, 0xffff0000, v115
	v_lshlrev_b32_e32 v4, 16, v115
	v_pk_mul_f32 v[4:5], v[10:11], v[4:5]
	v_cvt_pk_bf16_f32 v2, v2, v3
	v_cvt_pk_bf16_f32 v3, v4, v5
	ds_write_b64 v216, v[2:3] offset:96
	v_and_b32_e32 v3, 0xffff0000, v112
	v_lshlrev_b32_e32 v2, 16, v112
	v_pk_mul_f32 v[4:5], v[28:29], v[6:7] op_sel_hi:[1,0]
	v_pk_mul_f32 v[6:7], v[30:31], v[6:7] op_sel_hi:[1,0]
	v_pk_mul_f32 v[2:3], v[4:5], v[2:3]
	v_and_b32_e32 v5, 0xffff0000, v113
	v_lshlrev_b32_e32 v4, 16, v113
	v_pk_mul_f32 v[4:5], v[6:7], v[4:5]
	v_cvt_pk_bf16_f32 v2, v2, v3
	v_cvt_pk_bf16_f32 v3, v4, v5
	ds_write_b64 v216, v[2:3] offset:112
	s_waitcnt lgkmcnt(0)
	ds_read_b128 v[200:203], v217
	ds_read_b128 v[204:207], v217 offset:1152
	ds_read_b128 v[208:211], v217 offset:2304
	ds_read_b128 v[212:215], v217 offset:3456
	v_mov_b32_e32 v220, 0x4000
	v_mov_b32_e32 v221, 0
	s_waitcnt lgkmcnt(3)
	global_store_dwordx4 v[218:219], v[200:203], off nt
	v_lshl_add_u64 v[218:219], v[218:219], 0, v[220:221]
	s_waitcnt lgkmcnt(2)
	global_store_dwordx4 v[218:219], v[204:207], off nt
	v_lshl_add_u64 v[218:219], v[218:219], 0, v[220:221]
	s_waitcnt lgkmcnt(1)
	global_store_dwordx4 v[218:219], v[208:211], off nt
	v_lshl_add_u64 v[218:219], v[218:219], 0, v[220:221]
	s_waitcnt lgkmcnt(0)
	global_store_dwordx4 v[218:219], v[212:215], off nt
	s_barrier

.LBB0_871:
	s_or_b64 exec, exec, s[0:1]
	v_lshlrev_b32_e32 v15, 7, v169
	v_lshlrev_b64 v[16:17], 1, v[174:175]
	v_or_b32_e32 v14, v171, v192
	s_waitcnt lgkmcnt(0)
	v_lshl_add_u64 v[12:13], s[10:11], 0, v[16:17]
	v_lshlrev_b32_e32 v0, 1, v15
	v_lshlrev_b32_e32 v30, 2, v15
	v_ashrrev_i32_e32 v15, 31, v14
	v_lshl_add_u64 v[12:13], v[12:13], 0, v[0:1]
	v_lshlrev_b64 v[52:53], 1, v[14:15]
	v_lshl_add_u64 v[56:57], v[12:13], 0, v[52:53]
	s_barrier
	global_load_dwordx2 v[64:65], v[56:57], off
	v_mov_b32_e32 v31, v1
	v_lshl_add_u64 v[30:31], s[68:69], 0, v[30:31]
	v_lshl_add_u64 v[60:61], v[14:15], 2, v[30:31]
	global_load_dwordx4 v[12:15], v[60:61], off
	global_load_dwordx2 v[72:73], v[56:57], off offset:16
	global_load_dwordx4 v[30:33], v[60:61], off offset:32
	global_load_dwordx2 v[74:75], v[56:57], off offset:32
	global_load_dwordx4 v[40:43], v[60:61], off offset:64
	global_load_dwordx2 v[76:77], v[56:57], off offset:48
	global_load_dwordx4 v[44:47], v[60:61], off offset:96
	global_load_dwordx2 v[78:79], v[56:57], off offset:64
	global_load_dwordx4 v[48:51], v[60:61], off offset:128
	v_xor_b32_e32 v10, 64, v10
	v_lshl_add_u32 v54, v10, 2, v182
	ds_read_b32 v58, v11
	ds_read_b32 v59, v54
	v_lshl_add_u64 v[10:11], s[12:13], 0, v[16:17]
	v_lshl_add_u64 v[10:11], v[10:11], 0, v[0:1]
	global_load_dwordx2 v[16:17], v[56:57], off offset:80
	v_lshl_add_u64 v[10:11], v[10:11], 0, v[52:53]
	global_load_dwordx4 v[52:55], v[60:61], off offset:160
	s_waitcnt lgkmcnt(0)
	v_add_f32_e32 v0, v58, v59
	v_fmamk_f32 v0, v0, 0x3c000000, v186
	v_mul_f32_e32 v58, 0x4b800000, v0
	v_cmp_gt_f32_e32 vcc, s35, v0
	s_waitcnt vmcnt(11)
	v_and_b32_e32 v85, 0xffff0000, v64
	v_cndmask_b32_e32 v0, v0, v58, vcc
	global_load_dwordx2 v[80:81], v[56:57], off offset:96
	global_load_dwordx2 v[82:83], v[56:57], off offset:112
	s_nop 0
	global_load_dwordx4 v[56:59], v[60:61], off offset:192
	s_nop 0
	global_load_dwordx4 v[60:63], v[60:61], off offset:224
	v_rsq_f32_e32 v0, v0
	s_nop 0
	v_mul_f32_e32 v84, 0x45800000, v0
	v_cndmask_b32_e32 v0, v0, v84, vcc
	v_pk_mul_f32 v[66:67], v[66:67], v[0:1] op_sel_hi:[1,0]
	v_pk_mul_f32 v[68:69], v[68:69], v[0:1] op_sel_hi:[1,0]
	v_pk_mul_f32 v[70:71], v[70:71], v[0:1] op_sel_hi:[1,0]
	v_pk_mul_f32 v[38:39], v[38:39], v[0:1] op_sel_hi:[1,0]
	v_pk_mul_f32 v[36:37], v[36:37], v[0:1] op_sel_hi:[1,0]
	v_pk_mul_f32 v[34:35], v[34:35], v[0:1] op_sel_hi:[1,0]
	v_lshlrev_b32_e32 v84, 16, v64
	s_waitcnt vmcnt(14)
	v_pk_mul_f32 v[12:13], v[12:13], v[66:67]
	v_and_b32_e32 v67, 0xffff0000, v65
	v_lshlrev_b32_e32 v66, 16, v65
	v_pk_mul_f32 v[14:15], v[14:15], v[68:69]
	s_waitcnt vmcnt(13)
	v_and_b32_e32 v65, 0xffff0000, v72
	v_lshlrev_b32_e32 v64, 16, v72
	s_waitcnt vmcnt(12)
	v_pk_mul_f32 v[30:31], v[30:31], v[70:71]
	v_and_b32_e32 v69, 0xffff0000, v73
	v_lshlrev_b32_e32 v68, 16, v73
	v_pk_mul_f32 v[32:33], v[32:33], v[38:39]
	s_waitcnt vmcnt(11)
	v_and_b32_e32 v39, 0xffff0000, v74
	v_lshlrev_b32_e32 v38, 16, v74
	s_waitcnt vmcnt(10)
	v_pk_mul_f32 v[36:37], v[40:41], v[36:37]
	v_and_b32_e32 v41, 0xffff0000, v75
	v_lshlrev_b32_e32 v40, 16, v75
	v_pk_mul_f32 v[34:35], v[42:43], v[34:35]
	v_pk_mul_f32 v[12:13], v[12:13], v[84:85]
	v_pk_mul_f32 v[14:15], v[14:15], v[66:67]
	v_pk_mul_f32 v[30:31], v[30:31], v[64:65]
	v_pk_mul_f32 v[32:33], v[32:33], v[68:69]
	v_pk_mul_f32 v[36:37], v[36:37], v[38:39]
	v_pk_mul_f32 v[34:35], v[34:35], v[40:41]
	v_cvt_pk_bf16_f32 v12, v12, v13
	v_cvt_pk_bf16_f32 v13, v14, v15
	v_cvt_pk_bf16_f32 v14, v30, v31
	v_cvt_pk_bf16_f32 v15, v32, v33
	v_cvt_pk_bf16_f32 v30, v36, v37
	v_cvt_pk_bf16_f32 v31, v34, v35
	v_and_b32_e32 v233, 63, v172
	v_lshrrev_b32_e32 v232, 6, v172
	v_mul_u32_u24_e32 v232, 0x1200, v232
	v_add_u32_e32 v232, v232, v182
	v_add_u32_e32 v232, 0x3000, v232
	v_and_b32_e32 v244, 31, v233
	v_lshrrev_b32_e32 v245, 5, v233
	v_lshrrev_b32_e32 v246, 3, v233
	v_and_b32_e32 v247, 7, v233
	v_mul_u32_u24_e32 v248, 0x90, v246
	v_lshl_add_u32 v248, v247, 4, v248
	v_add_u32_e32 v233, v248, v232
	v_mul_u32_u24_e32 v248, 0x90, v244
	v_lshl_add_u32 v248, v245, 3, v248
	v_add_u32_e32 v232, v248, v232
	v_sub_u32_e32 v246, v246, v244
	v_lshlrev_b32_e32 v246, 11, v246
	v_lshl_add_u32 v246, v247, 4, v246
	v_lshlrev_b32_e32 v245, 3, v245
	v_sub_u32_e32 v246, v246, v245
	v_ashrrev_i32_e32 v247, 31, v246
	v_lshl_add_u64 v[244:245], v[10:11], 0, v[246:247]
	ds_write_b64 v232, v[12:13]
	ds_write_b64 v232, v[14:15] offset:16
	ds_write_b64 v232, v[30:31] offset:32
	v_pk_mul_f32 v[12:13], v[24:25], v[0:1] op_sel_hi:[1,0]
	v_pk_mul_f32 v[22:23], v[22:23], v[0:1] op_sel_hi:[1,0]
	s_waitcnt vmcnt(9)
	v_and_b32_e32 v43, 0xffff0000, v76
	v_lshlrev_b32_e32 v42, 16, v76
	s_waitcnt vmcnt(8)
	v_pk_mul_f32 v[12:13], v[12:13], v[44:45]
	v_and_b32_e32 v15, 0xffff0000, v77
	v_lshlrev_b32_e32 v14, 16, v77
	v_pk_mul_f32 v[22:23], v[22:23], v[46:47]
	v_pk_mul_f32 v[12:13], v[12:13], v[42:43]
	v_pk_mul_f32 v[14:15], v[22:23], v[14:15]
	v_cvt_pk_bf16_f32 v12, v12, v13
	v_cvt_pk_bf16_f32 v13, v14, v15
	v_pk_mul_f32 v[14:15], v[28:29], v[0:1] op_sel_hi:[1,0]
	ds_write_b64 v232, v[12:13] offset:48
	s_waitcnt vmcnt(7)
	v_and_b32_e32 v13, 0xffff0000, v78
	v_lshlrev_b32_e32 v12, 16, v78
	s_waitcnt vmcnt(6)
	v_pk_mul_f32 v[14:15], v[14:15], v[48:49]
	v_pk_mul_f32 v[22:23], v[26:27], v[0:1] op_sel_hi:[1,0]
	v_pk_mul_f32 v[12:13], v[14:15], v[12:13]
	v_and_b32_e32 v15, 0xffff0000, v79
	v_lshlrev_b32_e32 v14, 16, v79
	v_pk_mul_f32 v[22:23], v[22:23], v[50:51]
	v_cvt_pk_bf16_f32 v12, v12, v13
	v_pk_mul_f32 v[14:15], v[22:23], v[14:15]
	v_pk_mul_f32 v[8:9], v[8:9], v[0:1] op_sel_hi:[1,0]
	v_cvt_pk_bf16_f32 v13, v14, v15
	v_pk_mul_f32 v[14:15], v[20:21], v[0:1] op_sel_hi:[1,0]
	ds_write_b64 v232, v[12:13] offset:64
	s_waitcnt vmcnt(5)
	v_and_b32_e32 v13, 0xffff0000, v16
	v_lshlrev_b32_e32 v12, 16, v16
	s_waitcnt vmcnt(4)
	v_pk_mul_f32 v[14:15], v[14:15], v[52:53]
	v_pk_mul_f32 v[6:7], v[6:7], v[0:1] op_sel_hi:[1,0]
	v_pk_mul_f32 v[12:13], v[14:15], v[12:13]
	v_and_b32_e32 v15, 0xffff0000, v17
	v_lshlrev_b32_e32 v14, 16, v17
	v_pk_mul_f32 v[16:17], v[18:19], v[0:1] op_sel_hi:[1,0]
	v_cvt_pk_bf16_f32 v12, v12, v13
	v_pk_mul_f32 v[16:17], v[16:17], v[54:55]
	s_waitcnt vmcnt(1)
	v_pk_mul_f32 v[8:9], v[8:9], v[56:57]
	v_pk_mul_f32 v[14:15], v[16:17], v[14:15]
	v_pk_mul_f32 v[6:7], v[6:7], v[58:59]
	v_cvt_pk_bf16_f32 v13, v14, v15
	ds_write_b64 v232, v[12:13] offset:80
	v_and_b32_e32 v13, 0xffff0000, v80
	v_lshlrev_b32_e32 v12, 16, v80
	v_pk_mul_f32 v[8:9], v[8:9], v[12:13]
	v_and_b32_e32 v13, 0xffff0000, v81
	v_lshlrev_b32_e32 v12, 16, v81
	v_pk_mul_f32 v[6:7], v[6:7], v[12:13]
	v_pk_mul_f32 v[4:5], v[4:5], v[0:1] op_sel_hi:[1,0]
	v_cvt_pk_bf16_f32 v8, v8, v9
	v_cvt_pk_bf16_f32 v9, v6, v7
	v_and_b32_e32 v7, 0xffff0000, v82
	v_lshlrev_b32_e32 v6, 16, v82
	s_waitcnt vmcnt(0)
	v_pk_mul_f32 v[4:5], v[4:5], v[60:61]
	v_pk_mul_f32 v[2:3], v[2:3], v[0:1] op_sel_hi:[1,0]
	v_pk_mul_f32 v[4:5], v[4:5], v[6:7]
	v_and_b32_e32 v7, 0xffff0000, v83
	v_lshlrev_b32_e32 v6, 16, v83
	v_pk_mul_f32 v[2:3], v[2:3], v[62:63]
	v_cvt_pk_bf16_f32 v4, v4, v5
	v_pk_mul_f32 v[2:3], v[2:3], v[6:7]
	ds_write_b64 v232, v[8:9] offset:96
	v_cvt_pk_bf16_f32 v5, v2, v3
	ds_write_b64 v232, v[4:5] offset:112
	s_waitcnt lgkmcnt(0)
	ds_read_b128 v[200:203], v233
	ds_read_b128 v[204:207], v233 offset:1152
	ds_read_b128 v[208:211], v233 offset:2304
	ds_read_b128 v[212:215], v233 offset:3456
	v_mov_b32_e32 v246, 0x4000
	v_mov_b32_e32 v247, 0
	s_waitcnt lgkmcnt(3)
	global_store_dwordx4 v[244:245], v[200:203], off nt
	v_lshl_add_u64 v[244:245], v[244:245], 0, v[246:247]
	s_waitcnt lgkmcnt(2)
	global_store_dwordx4 v[244:245], v[204:207], off nt
	v_lshl_add_u64 v[244:245], v[244:245], 0, v[246:247]
	s_waitcnt lgkmcnt(1)
	global_store_dwordx4 v[244:245], v[208:211], off nt
	v_lshl_add_u64 v[244:245], v[244:245], 0, v[246:247]
	s_waitcnt lgkmcnt(0)
	global_store_dwordx4 v[244:245], v[212:215], off nt

.LBB0_907:
	s_or_b64 exec, exec, s[18:19]
	v_lshrrev_b32_e32 v216, 6, v172
	v_mul_u32_u24_e32 v216, 0x1200, v216
	v_add_u32_e32 v216, v216, v182
	v_add_u32_e32 v216, 0x3000, v216
	v_lshrrev_b32_e32 v220, 3, v198
	v_and_b32_e32 v221, 7, v198
	v_mul_u32_u24_e32 v217, 0x90, v220
	v_lshl_add_u32 v217, v221, 4, v217
	v_add_u32_e32 v217, v217, v216
	v_lshrrev_b32_e32 v220, 4, v198
	v_and_b32_e32 v221, 15, v198
	v_mul_u32_u24_e32 v222, 0x90, v220
	v_lshl_add_u32 v222, v221, 3, v222
	v_add_u32_e32 v222, v222, v216
	v_and_b32_e32 v218, 31, v198
	v_lshrrev_b32_e32 v219, 5, v198
	v_mul_u32_u24_e32 v223, 0x90, v218
	v_lshl_add_u32 v223, v219, 3, v223
	v_add_u32_e32 v216, v223, v216
	ds_write_b128 v217, v[104:107]
	ds_write_b128 v217, v[108:111] offset:1152
	ds_write_b128 v217, v[112:115] offset:2304
	ds_write_b64 v222, v[116:117] offset:3456
	ds_write_b64 v222, v[122:123] offset:4032
	s_waitcnt lgkmcnt(0)
	ds_read_b64 v[122:123], v216
	ds_read_b64 v[116:117], v216 offset:16
	ds_read_b64 v[114:115], v216 offset:32
	ds_read_b64 v[112:113], v216 offset:48
	ds_read_b64 v[110:111], v216 offset:64
	ds_read_b64 v[108:109], v216 offset:80
	ds_read_b64 v[106:107], v216 offset:96
	ds_read_b64 v[104:105], v216 offset:112
	s_waitcnt lgkmcnt(0)
	ds_bpermute_b32 v0, v234, v10
	s_waitcnt vmcnt(6)
	v_and_b32_e32 v5, 0xffff0000, v122
	v_lshlrev_b32_e32 v4, 16, v122
	v_lshl_add_u64 v[2:3], v[118:119], 1, v[120:121]
	s_waitcnt lgkmcnt(0)
	v_add_f32_e32 v0, v10, v0
	v_max_f32_e32 v0, 0xda24260, v0
	v_div_scale_f32 v6, s[18:19], v0, v0, 1.0
	v_rcp_f32_e32 v7, v6
	v_div_scale_f32 v8, vcc, 1.0, v0, 1.0
	s_mov_b64 s[18:19], 0x16f80400
	v_fma_f32 v9, -v6, v7, 1.0
	v_fmac_f32_e32 v7, v9, v7
	v_mul_f32_e32 v9, v8, v7
	v_fma_f32 v10, -v6, v9, v8
	v_fmac_f32_e32 v9, v10, v7
	v_fma_f32 v6, -v6, v9, v8
	v_div_fmas_f32 v6, v6, v7, v9
	v_div_fixup_f32 v6, v6, v0, 1.0
	v_pk_mul_f32 v[8:9], v[32:33], v[6:7] op_sel_hi:[1,0]
	v_pk_mul_f32 v[10:11], v[34:35], v[6:7] op_sel_hi:[1,0]
	v_pk_mul_f32 v[4:5], v[8:9], v[4:5]
	v_and_b32_e32 v9, 0xffff0000, v123
	v_lshlrev_b32_e32 v8, 16, v123
	v_lshlrev_b32_e32 v0, 1, v125
	v_pk_mul_f32 v[8:9], v[10:11], v[8:9]
	v_lshl_add_u64 v[2:3], v[2:3], 0, v[0:1]
	v_cvt_pk_bf16_f32 v4, v4, v5
	v_cvt_pk_bf16_f32 v5, v8, v9
	v_lshl_add_u64 v[8:9], v[2:3], 0, s[18:19]
	s_mov_b32 s18, 0x16f80000
	v_add_co_u32_e32 v2, vcc, s18, v2
	v_pk_mul_f32 v[10:11], v[38:39], v[6:7] op_sel_hi:[1,0]
	s_nop 0
	v_addc_co_u32_e32 v3, vcc, 0, v3, vcc
	v_lshrrev_b32_e32 v216, 6, v172
	v_mul_u32_u24_e32 v216, 0x1200, v216
	v_add_u32_e32 v216, v216, v182
	v_add_u32_e32 v216, 0x3000, v216
	v_and_b32_e32 v218, 31, v198
	v_lshrrev_b32_e32 v219, 5, v198
	v_lshrrev_b32_e32 v220, 3, v198
	v_and_b32_e32 v221, 7, v198
	v_mul_u32_u24_e32 v222, 0x90, v220
	v_lshl_add_u32 v222, v221, 4, v222
	v_add_u32_e32 v217, v222, v216
	v_mul_u32_u24_e32 v222, 0x90, v218
	v_lshl_add_u32 v222, v219, 3, v222
	v_add_u32_e32 v216, v222, v216
	v_sub_u32_e32 v220, v220, v218
	v_lshlrev_b32_e32 v220, 11, v220
	v_lshl_add_u32 v220, v221, 4, v220
	v_lshlrev_b32_e32 v219, 3, v219
	v_sub_u32_e32 v220, v220, v219
	v_ashrrev_i32_e32 v221, 31, v220
	v_lshl_add_u64 v[218:219], v[8:9], 0, v[220:221]
	ds_write_b64 v216, v[4:5]
	v_and_b32_e32 v3, 0xffff0000, v116
	v_lshlrev_b32_e32 v2, 16, v116
	v_pk_mul_f32 v[4:5], v[36:37], v[6:7] op_sel_hi:[1,0]
	s_nop 0
	v_pk_mul_f32 v[2:3], v[4:5], v[2:3]
	v_and_b32_e32 v5, 0xffff0000, v117
	v_lshlrev_b32_e32 v4, 16, v117
	v_pk_mul_f32 v[4:5], v[10:11], v[4:5]
	v_cvt_pk_bf16_f32 v2, v2, v3
	v_cvt_pk_bf16_f32 v3, v4, v5
	ds_write_b64 v216, v[2:3] offset:16
	v_and_b32_e32 v3, 0xffff0000, v114
	v_lshlrev_b32_e32 v2, 16, v114
	v_pk_mul_f32 v[4:5], v[40:41], v[6:7] op_sel_hi:[1,0]
	v_pk_mul_f32 v[10:11], v[42:43], v[6:7] op_sel_hi:[1,0]
	v_pk_mul_f32 v[2:3], v[4:5], v[2:3]
	v_and_b32_e32 v5, 0xffff0000, v115
	v_lshlrev_b32_e32 v4, 16, v115
	v_pk_mul_f32 v[4:5], v[10:11], v[4:5]
	v_cvt_pk_bf16_f32 v2, v2, v3
	v_cvt_pk_bf16_f32 v3, v4, v5
	ds_write_b64 v216, v[2:3] offset:32
	v_and_b32_e32 v3, 0xffff0000, v112
	v_lshlrev_b32_e32 v2, 16, v112
	v_pk_mul_f32 v[4:5], v[44:45], v[6:7] op_sel_hi:[1,0]
	v_pk_mul_f32 v[10:11], v[46:47], v[6:7] op_sel_hi:[1,0]
	v_pk_mul_f32 v[2:3], v[4:5], v[2:3]
	v_and_b32_e32 v5, 0xffff0000, v113
	v_lshlrev_b32_e32 v4, 16, v113
	v_pk_mul_f32 v[4:5], v[10:11], v[4:5]
	v_cvt_pk_bf16_f32 v2, v2, v3
	v_cvt_pk_bf16_f32 v3, v4, v5
	ds_write_b64 v216, v[2:3] offset:48
	v_and_b32_e32 v3, 0xffff0000, v110
	v_lshlrev_b32_e32 v2, 16, v110
	v_pk_mul_f32 v[4:5], v[16:17], v[6:7] op_sel_hi:[1,0]
	v_pk_mul_f32 v[10:11], v[18:19], v[6:7] op_sel_hi:[1,0]
	v_pk_mul_f32 v[2:3], v[4:5], v[2:3]
	v_and_b32_e32 v5, 0xffff0000, v111
	v_lshlrev_b32_e32 v4, 16, v111
	v_pk_mul_f32 v[4:5], v[10:11], v[4:5]
	v_cvt_pk_bf16_f32 v2, v2, v3
	v_cvt_pk_bf16_f32 v3, v4, v5
	ds_write_b64 v216, v[2:3] offset:64
	v_and_b32_e32 v3, 0xffff0000, v108
	v_lshlrev_b32_e32 v2, 16, v108
	v_pk_mul_f32 v[4:5], v[20:21], v[6:7] op_sel_hi:[1,0]
	v_pk_mul_f32 v[10:11], v[22:23], v[6:7] op_sel_hi:[1,0]
	v_pk_mul_f32 v[2:3], v[4:5], v[2:3]
	v_and_b32_e32 v5, 0xffff0000, v109
	v_lshlrev_b32_e32 v4, 16, v109
	v_pk_mul_f32 v[4:5], v[10:11], v[4:5]
	v_cvt_pk_bf16_f32 v2, v2, v3
	v_cvt_pk_bf16_f32 v3, v4, v5
	ds_write_b64 v216, v[2:3] offset:80
	s_waitcnt vmcnt(5)
	v_and_b32_e32 v3, 0xffff0000, v106
	v_lshlrev_b32_e32 v2, 16, v106
	v_pk_mul_f32 v[4:5], v[24:25], v[6:7] op_sel_hi:[1,0]
	v_pk_mul_f32 v[10:11], v[26:27], v[6:7] op_sel_hi:[1,0]
	v_pk_mul_f32 v[2:3], v[4:5], v[2:3]
	v_and_b32_e32 v5, 0xffff0000, v107
	v_lshlrev_b32_e32 v4, 16, v107
	v_pk_mul_f32 v[4:5], v[10:11], v[4:5]
	v_cvt_pk_bf16_f32 v2, v2, v3
	v_cvt_pk_bf16_f32 v3, v4, v5
	ds_write_b64 v216, v[2:3] offset:96
	s_waitcnt vmcnt(4)
	v_and_b32_e32 v3, 0xffff0000, v104
	v_lshlrev_b32_e32 v2, 16, v104
	v_pk_mul_f32 v[4:5], v[28:29], v[6:7] op_sel_hi:[1,0]
	v_pk_mul_f32 v[6:7], v[30:31], v[6:7] op_sel_hi:[1,0]
	v_pk_mul_f32 v[2:3], v[4:5], v[2:3]
	v_and_b32_e32 v5, 0xffff0000, v105
	v_lshlrev_b32_e32 v4, 16, v105
	v_pk_mul_f32 v[4:5], v[6:7], v[4:5]
	v_cvt_pk_bf16_f32 v2, v2, v3
	v_cvt_pk_bf16_f32 v3, v4, v5
	ds_write_b64 v216, v[2:3] offset:112
	s_waitcnt lgkmcnt(0)
	ds_read_b128 v[200:203], v217
	ds_read_b128 v[204:207], v217 offset:1152
	ds_read_b128 v[208:211], v217 offset:2304
	ds_read_b128 v[212:215], v217 offset:3456
	v_mov_b32_e32 v220, 0x4000
	v_mov_b32_e32 v221, 0
	s_waitcnt lgkmcnt(3)
	global_store_dwordx4 v[218:219], v[200:203], off nt
	v_lshl_add_u64 v[218:219], v[218:219], 0, v[220:221]
	s_waitcnt lgkmcnt(2)
	global_store_dwordx4 v[218:219], v[204:207], off nt
	v_lshl_add_u64 v[218:219], v[218:219], 0, v[220:221]
	s_waitcnt lgkmcnt(1)
	global_store_dwordx4 v[218:219], v[208:211], off nt
	v_lshl_add_u64 v[218:219], v[218:219], 0, v[220:221]
	s_waitcnt lgkmcnt(0)
	global_store_dwordx4 v[218:219], v[212:215], off nt
	s_barrier
